# P1 in-proj epilogue: 8 per-row rstd loads hoisted in front of the store rounds (quarter-row loads + permlane reduce), no vmcnt(0) between rounds
# speedup vs baseline: 1.0138x; 1.0101x over previous
;     __device__ __forceinline__ void operator()(const f32x4 (&acc)[2][2][4][2], const Unit& u, int wr, int wc, int fr, int fq) const {
;         const int row0 = u.pm * BM + wr * 64 + fr, col0 = u.pn * BM + wc * 32 + 8 * fq;
; #pragma unroll
;         for (int ai = 0; ai < 2; ++ai)
; #pragma unroll
;             for (int m = 0; m < 4; ++m) {
;                 const int row = row0 + ai * HALF + m * 16;
;                 const f32x4* sp = (const f32x4*)(ss + (size_t)row * 16);
;                 const f32x4 a0 = sp[0], a1 = sp[1], a2 = sp[2], a3 = sp[3];
;                 const float tot = ((a0.x + a0.y) + (a0.z + a0.w)) + ((a1.x + a1.y) + (a1.z + a1.w)) + ((a2.x + a2.y) + (a2.z + a2.w)) + ((a3.x + a3.y) + (a3.z + a3.w));
;                 const float rs = rsqrtf(tot * (1.0f / 1024.0f) + 1e-6f);
;                 bf16_t* rowp = O + (size_t)row * ldc + col0;
; #pragma unroll
;                 for (int bj = 0; bj < 2; ++bj) {
;                     f32x4 v0 = acc[ai][bj][m][0] * rs, v1 = acc[ai][bj][m][1] * rs;
.LBB0_429:
	v_lshl_add_u32 v154, s24, 8, v156
	v_ashrrev_i32_e32 v155, 31, v154
	v_lshlrev_b64 v[234:235], 6, v[154:155]
	v_and_or_b32 v234, v204, 48, v234
	v_lshl_add_u64 v[234:235], s[90:91], 0, v[234:235]
	v_mov_b32_e32 v236, 0x2000
	v_mov_b32_e32 v237, 0
	v_lshl_add_u64 v[236:237], v[234:235], 0, v[236:237]
	global_load_dwordx4 v[180:183], v[234:235], off
	global_load_dwordx4 v[184:187], v[234:235], off offset:1024
	global_load_dwordx4 v[188:191], v[234:235], off offset:2048
	global_load_dwordx4 v[192:195], v[234:235], off offset:3072
	global_load_dwordx4 v[196:199], v[236:237], off
	global_load_dwordx4 v[200:203], v[236:237], off offset:1024
	global_load_dwordx4 v[216:219], v[236:237], off offset:2048
	global_load_dwordx4 v[220:223], v[236:237], off offset:3072
	v_lshl_or_b32 v152, s25, 8, v158
	v_ashrrev_i32_e32 v153, 31, v152
	v_lshlrev_b64 v[152:153], 1, v[152:153]
	v_bfe_u32 v228, v204, 2, 4
	v_and_b32_e32 v229, 15, v204
	v_sub_u32_e32 v229, v228, v229
	v_mul_i32_i24_e32 v229, s49, v229
	v_and_b32_e32 v231, 3, v204
	v_bfe_u32 v232, v204, 4, 2
	v_sub_u32_e32 v232, v231, v232
	v_lshl_add_u32 v229, v232, 3, v229
	v_lshlrev_b32_e32 v232, 1, v229
	v_ashrrev_i32_e32 v233, 31, v232
	v_lshl_add_u64 v[152:153], v[152:153], 0, v[232:233]
	v_lshl_add_u32 v230, v231, 4, v228
	v_lshlrev_b32_e32 v230, 2, v230
	v_readlane_b32 s76, v250, 21
	v_readlane_b32 s92, v250, 23
	v_readlane_b32 s96, v250, 25
	v_readlane_b32 s77, v250, 22
	v_readlane_b32 s93, v250, 24
	v_readlane_b32 s97, v250, 26
	v_mad_i64_i32 v[162:163], s[24:25], v154, s49, 0
	v_lshl_add_u64 v[162:163], v[162:163], 1, s[78:79]
	v_lshl_add_u64 v[162:163], v[162:163], 0, v[152:153]
	s_waitcnt vmcnt(0)
	v_add_f32_e32 v180, v180, v181
	v_add_f32_e32 v182, v182, v183
	v_add_f32_e32 v184, v184, v185
	v_add_f32_e32 v186, v186, v187
	v_add_f32_e32 v188, v188, v189
	v_add_f32_e32 v190, v190, v191
	v_add_f32_e32 v192, v192, v193
	v_add_f32_e32 v194, v194, v195
	v_add_f32_e32 v196, v196, v197
	v_add_f32_e32 v198, v198, v199
	v_add_f32_e32 v200, v200, v201
	v_add_f32_e32 v202, v202, v203
	v_add_f32_e32 v216, v216, v217
	v_add_f32_e32 v218, v218, v219
	v_add_f32_e32 v220, v220, v221
	v_add_f32_e32 v222, v222, v223
	v_add_f32_e32 v180, v180, v182
	v_add_f32_e32 v184, v184, v186
	v_add_f32_e32 v188, v188, v190
	v_add_f32_e32 v192, v192, v194
	v_add_f32_e32 v196, v196, v198
	v_add_f32_e32 v200, v200, v202
	v_add_f32_e32 v216, v216, v218
	v_add_f32_e32 v220, v220, v222
	v_mov_b32_e32 v181, v180
	v_mov_b32_e32 v185, v184
	v_mov_b32_e32 v189, v188
	v_mov_b32_e32 v193, v192
	v_mov_b32_e32 v197, v196
	v_mov_b32_e32 v201, v200
	v_mov_b32_e32 v217, v216
	v_mov_b32_e32 v221, v220
	s_nop 1
	v_permlane16_swap_b32_e32 v180, v181
	v_permlane16_swap_b32_e32 v184, v185
	v_permlane16_swap_b32_e32 v188, v189
	v_permlane16_swap_b32_e32 v192, v193
	v_permlane16_swap_b32_e32 v196, v197
	v_permlane16_swap_b32_e32 v200, v201
	v_permlane16_swap_b32_e32 v216, v217
	v_permlane16_swap_b32_e32 v220, v221
	v_add_f32_e32 v180, v180, v181
	v_add_f32_e32 v184, v184, v185
	v_add_f32_e32 v188, v188, v189
	v_add_f32_e32 v192, v192, v193
	v_add_f32_e32 v196, v196, v197
	v_add_f32_e32 v200, v200, v201
	v_add_f32_e32 v216, v216, v217
	v_add_f32_e32 v220, v220, v221
	v_mov_b32_e32 v181, v180
	v_mov_b32_e32 v185, v184
	v_mov_b32_e32 v189, v188
	v_mov_b32_e32 v193, v192
	v_mov_b32_e32 v197, v196
	v_mov_b32_e32 v201, v200
	v_mov_b32_e32 v217, v216
	v_mov_b32_e32 v221, v220
	s_nop 1
	v_permlane32_swap_b32_e32 v180, v181
	v_permlane32_swap_b32_e32 v184, v185
	v_permlane32_swap_b32_e32 v188, v189
	v_permlane32_swap_b32_e32 v192, v193
	v_permlane32_swap_b32_e32 v196, v197
	v_permlane32_swap_b32_e32 v200, v201
	v_permlane32_swap_b32_e32 v216, v217
	v_permlane32_swap_b32_e32 v220, v221
	v_add_f32_e32 v180, v180, v181
	v_add_f32_e32 v184, v184, v185
	v_add_f32_e32 v188, v188, v189
	v_add_f32_e32 v192, v192, v193
	v_add_f32_e32 v196, v196, v197
	v_add_f32_e32 v200, v200, v201
	v_add_f32_e32 v216, v216, v217
	v_add_f32_e32 v220, v220, v221
	v_fmamk_f32 v180, v180, 0x3a800000, v137
	v_cmp_gt_f32_e32 vcc, s4, v180
	v_mul_f32_e32 v181, 0x4b800000, v180
	s_nop 0
	v_cndmask_b32_e32 v180, v180, v181, vcc
	v_rsq_f32_e32 v180, v180
	s_nop 0
	v_mul_f32_e32 v181, 0x45800000, v180
	v_cndmask_b32_e32 v180, v180, v181, vcc
	v_fmamk_f32 v184, v184, 0x3a800000, v137
	v_cmp_gt_f32_e32 vcc, s4, v184
	v_mul_f32_e32 v185, 0x4b800000, v184
	s_nop 0
	v_cndmask_b32_e32 v184, v184, v185, vcc
	v_rsq_f32_e32 v184, v184
	s_nop 0
	v_mul_f32_e32 v185, 0x45800000, v184
	v_cndmask_b32_e32 v184, v184, v185, vcc
	v_fmamk_f32 v188, v188, 0x3a800000, v137
	v_cmp_gt_f32_e32 vcc, s4, v188
	v_mul_f32_e32 v189, 0x4b800000, v188
	s_nop 0
	v_cndmask_b32_e32 v188, v188, v189, vcc
	v_rsq_f32_e32 v188, v188
	s_nop 0
	v_mul_f32_e32 v189, 0x45800000, v188
	v_cndmask_b32_e32 v188, v188, v189, vcc
	v_fmamk_f32 v192, v192, 0x3a800000, v137
	v_cmp_gt_f32_e32 vcc, s4, v192
	v_mul_f32_e32 v193, 0x4b800000, v192
	s_nop 0
	v_cndmask_b32_e32 v192, v192, v193, vcc
	v_rsq_f32_e32 v192, v192
	s_nop 0
	v_mul_f32_e32 v193, 0x45800000, v192
	v_cndmask_b32_e32 v192, v192, v193, vcc
	v_fmamk_f32 v196, v196, 0x3a800000, v137
	v_cmp_gt_f32_e32 vcc, s4, v196
	v_mul_f32_e32 v197, 0x4b800000, v196
	s_nop 0
	v_cndmask_b32_e32 v196, v196, v197, vcc
	v_rsq_f32_e32 v196, v196
	s_nop 0
	v_mul_f32_e32 v197, 0x45800000, v196
	v_cndmask_b32_e32 v196, v196, v197, vcc
	v_fmamk_f32 v200, v200, 0x3a800000, v137
	v_cmp_gt_f32_e32 vcc, s4, v200
	v_mul_f32_e32 v201, 0x4b800000, v200
	s_nop 0
	v_cndmask_b32_e32 v200, v200, v201, vcc
	v_rsq_f32_e32 v200, v200
	s_nop 0
	v_mul_f32_e32 v201, 0x45800000, v200
	v_cndmask_b32_e32 v200, v200, v201, vcc
; __device__ __forceinline__ unsigned cvt_pk_bf16(float lo, float hi) { unsigned r; asm volatile("v_cvt_pk_bf16_f32 %0, %1, %2" : "=v"(r) : "v"(lo), "v"(hi)); return r; }
;     __device__ __forceinline__ void operator()(const f32x4 (&acc)[2][2][4][2], const Unit& u, int wr, int wc, int fr, int fq) const {
;     ...
;                 const float rs = rsqrtf(tot * (1.0f / 1024.0f) + 1e-6f);
;                 bf16_t* rowp = O + (size_t)row * ldc + col0;
; #pragma unroll
;                 for (int bj = 0; bj < 2; ++bj) {
;                     f32x4 v0 = acc[ai][bj][m][0] * rs, v1 = acc[ai][bj][m][1] * rs;
;                     if (ACT == 1) {
; #pragma unroll
;                         for (int e = 0; e < 4; ++e) { float a = fmaxf(v0[e], 0.f); v0[e] = a * a; float b = fmaxf(v1[e], 0.f); v1[e] = b * b; }
;                     }
;                     u32x4 w; w.x = cvt_pk_bf16(v0[0], v0[1]); w.y = cvt_pk_bf16(v0[2], v0[3]); w.z = cvt_pk_bf16(v1[0], v1[1]); w.w = cvt_pk_bf16(v1[2], v1[3]);
;                     *(u32x4*)(rowp + bj * HALF) = w;
	v_fmamk_f32 v216, v216, 0x3a800000, v137
	v_cmp_gt_f32_e32 vcc, s4, v216
	v_mul_f32_e32 v217, 0x4b800000, v216
	s_nop 0
	v_cndmask_b32_e32 v216, v216, v217, vcc
	v_rsq_f32_e32 v216, v216
	s_nop 0
	v_mul_f32_e32 v217, 0x45800000, v216
	v_cndmask_b32_e32 v216, v216, v217, vcc
	v_fmamk_f32 v220, v220, 0x3a800000, v137
	v_cmp_gt_f32_e32 vcc, s4, v220
	v_mul_f32_e32 v221, 0x4b800000, v220
	s_nop 0
	v_cndmask_b32_e32 v220, v220, v221, vcc
	v_rsq_f32_e32 v220, v220
	s_nop 0
	v_mul_f32_e32 v221, 0x45800000, v220
	v_cndmask_b32_e32 v220, v220, v221, vcc
	v_mov_b32_e32 v160, v180
	v_pk_mul_f32 v[126:127], v[126:127], v[160:161] op_sel_hi:[1,0]
	v_pk_mul_f32 v[124:125], v[124:125], v[160:161] op_sel_hi:[1,0]
	v_pk_mul_f32 v[164:165], v[122:123], v[160:161] op_sel_hi:[1,0]
	v_pk_mul_f32 v[122:123], v[120:121], v[160:161] op_sel_hi:[1,0]
	v_cvt_pk_bf16_f32 v120, v124, v125
	v_cvt_pk_bf16_f32 v121, v126, v127
	v_pk_mul_f32 v[118:119], v[118:119], v[160:161] op_sel_hi:[1,0]
	v_cvt_pk_bf16_f32 v122, v122, v123
	v_cvt_pk_bf16_f32 v123, v164, v165
	ds_bpermute_b32 v208, v230, v120
	ds_bpermute_b32 v209, v230, v121
	ds_bpermute_b32 v210, v230, v122
	ds_bpermute_b32 v211, v230, v123
	v_pk_mul_f32 v[116:117], v[116:117], v[160:161] op_sel_hi:[1,0]
	s_nop 0
	v_pk_mul_f32 v[120:121], v[114:115], v[160:161] op_sel_hi:[1,0]
	v_pk_mul_f32 v[114:115], v[112:113], v[160:161] op_sel_hi:[1,0]
	v_or_b32_e32 v160, 16, v154
	v_cvt_pk_bf16_f32 v112, v116, v117
	v_cvt_pk_bf16_f32 v113, v118, v119
	v_ashrrev_i32_e32 v161, 31, v160
	v_cvt_pk_bf16_f32 v114, v114, v115
	v_cvt_pk_bf16_f32 v115, v120, v121
	ds_bpermute_b32 v212, v230, v112
	ds_bpermute_b32 v213, v230, v113
	ds_bpermute_b32 v214, v230, v114
	ds_bpermute_b32 v215, v230, v115
	s_waitcnt lgkmcnt(4)
	global_store_dwordx4 v[162:163], v[208:211], off
	s_waitcnt lgkmcnt(0)
	global_store_dwordx4 v[162:163], v[212:215], off offset:256
	s_nop 1
	v_mad_i64_i32 v[114:115], s[24:25], v160, s49, 0
	v_lshl_add_u64 v[114:115], v[114:115], 1, s[78:79]
	v_lshl_add_u64 v[114:115], v[114:115], 0, v[152:153]
	v_mov_b32_e32 v112, v184
	v_pk_mul_f32 v[110:111], v[110:111], v[112:113] op_sel_hi:[1,0]
	v_pk_mul_f32 v[108:109], v[108:109], v[112:113] op_sel_hi:[1,0]
	v_pk_mul_f32 v[116:117], v[106:107], v[112:113] op_sel_hi:[1,0]
	v_pk_mul_f32 v[106:107], v[104:105], v[112:113] op_sel_hi:[1,0]
	v_cvt_pk_bf16_f32 v104, v108, v109
	v_cvt_pk_bf16_f32 v105, v110, v111
	v_pk_mul_f32 v[102:103], v[102:103], v[112:113] op_sel_hi:[1,0]
	v_cvt_pk_bf16_f32 v106, v106, v107
	v_cvt_pk_bf16_f32 v107, v116, v117
	ds_bpermute_b32 v208, v230, v104
	ds_bpermute_b32 v209, v230, v105
	ds_bpermute_b32 v210, v230, v106
	ds_bpermute_b32 v211, v230, v107
	v_pk_mul_f32 v[100:101], v[100:101], v[112:113] op_sel_hi:[1,0]
	s_nop 0
	v_pk_mul_f32 v[104:105], v[98:99], v[112:113] op_sel_hi:[1,0]
	v_pk_mul_f32 v[98:99], v[96:97], v[112:113] op_sel_hi:[1,0]
	v_or_b32_e32 v112, 32, v154
	v_cvt_pk_bf16_f32 v96, v100, v101
	v_cvt_pk_bf16_f32 v97, v102, v103
	v_ashrrev_i32_e32 v113, 31, v112
	v_cvt_pk_bf16_f32 v98, v98, v99
	v_cvt_pk_bf16_f32 v99, v104, v105
	ds_bpermute_b32 v212, v230, v96
	ds_bpermute_b32 v213, v230, v97
	ds_bpermute_b32 v214, v230, v98
	ds_bpermute_b32 v215, v230, v99
	s_waitcnt lgkmcnt(4)
	global_store_dwordx4 v[114:115], v[208:211], off
	s_waitcnt lgkmcnt(0)
	global_store_dwordx4 v[114:115], v[212:215], off offset:256
	s_nop 1
	v_mad_i64_i32 v[98:99], s[24:25], v112, s49, 0
	v_lshl_add_u64 v[98:99], v[98:99], 1, s[78:79]
	v_lshl_add_u64 v[98:99], v[98:99], 0, v[152:153]
	v_mov_b32_e32 v96, v188
	v_pk_mul_f32 v[94:95], v[94:95], v[96:97] op_sel_hi:[1,0]
	v_pk_mul_f32 v[92:93], v[92:93], v[96:97] op_sel_hi:[1,0]
	v_pk_mul_f32 v[100:101], v[90:91], v[96:97] op_sel_hi:[1,0]
	v_pk_mul_f32 v[90:91], v[88:89], v[96:97] op_sel_hi:[1,0]
	v_cvt_pk_bf16_f32 v88, v92, v93
	v_cvt_pk_bf16_f32 v89, v94, v95
	v_pk_mul_f32 v[86:87], v[86:87], v[96:97] op_sel_hi:[1,0]
	v_cvt_pk_bf16_f32 v90, v90, v91
	v_cvt_pk_bf16_f32 v91, v100, v101
	ds_bpermute_b32 v208, v230, v88
	ds_bpermute_b32 v209, v230, v89
	ds_bpermute_b32 v210, v230, v90
	ds_bpermute_b32 v211, v230, v91
	v_pk_mul_f32 v[84:85], v[84:85], v[96:97] op_sel_hi:[1,0]
	s_nop 0
	v_pk_mul_f32 v[88:89], v[82:83], v[96:97] op_sel_hi:[1,0]
	v_pk_mul_f32 v[82:83], v[80:81], v[96:97] op_sel_hi:[1,0]
	v_or_b32_e32 v96, 48, v154
	v_cvt_pk_bf16_f32 v80, v84, v85
	v_cvt_pk_bf16_f32 v81, v86, v87
	v_ashrrev_i32_e32 v97, 31, v96
	v_cvt_pk_bf16_f32 v82, v82, v83
	v_cvt_pk_bf16_f32 v83, v88, v89
	ds_bpermute_b32 v212, v230, v80
	ds_bpermute_b32 v213, v230, v81
	ds_bpermute_b32 v214, v230, v82
	ds_bpermute_b32 v215, v230, v83
	s_waitcnt lgkmcnt(4)
	global_store_dwordx4 v[98:99], v[208:211], off
	s_waitcnt lgkmcnt(0)
	global_store_dwordx4 v[98:99], v[212:215], off offset:256
	s_nop 1
	v_mad_i64_i32 v[82:83], s[24:25], v96, s49, 0
	v_lshl_add_u64 v[82:83], v[82:83], 1, s[78:79]
	v_lshl_add_u64 v[82:83], v[82:83], 0, v[152:153]
	v_mov_b32_e32 v80, v192
	v_pk_mul_f32 v[78:79], v[78:79], v[80:81] op_sel_hi:[1,0]
	v_pk_mul_f32 v[76:77], v[76:77], v[80:81] op_sel_hi:[1,0]
	v_pk_mul_f32 v[84:85], v[74:75], v[80:81] op_sel_hi:[1,0]
	v_pk_mul_f32 v[74:75], v[72:73], v[80:81] op_sel_hi:[1,0]
	v_cvt_pk_bf16_f32 v72, v76, v77
	v_cvt_pk_bf16_f32 v73, v78, v79
	v_pk_mul_f32 v[70:71], v[70:71], v[80:81] op_sel_hi:[1,0]
	v_cvt_pk_bf16_f32 v74, v74, v75
	v_cvt_pk_bf16_f32 v75, v84, v85
	ds_bpermute_b32 v208, v230, v72
	ds_bpermute_b32 v209, v230, v73
	ds_bpermute_b32 v210, v230, v74
	ds_bpermute_b32 v211, v230, v75
	v_pk_mul_f32 v[68:69], v[68:69], v[80:81] op_sel_hi:[1,0]
	s_nop 0
	v_pk_mul_f32 v[72:73], v[66:67], v[80:81] op_sel_hi:[1,0]
	v_pk_mul_f32 v[66:67], v[64:65], v[80:81] op_sel_hi:[1,0]
	v_add_u32_e32 v80, 0x80, v154
	v_cvt_pk_bf16_f32 v64, v68, v69
	v_cvt_pk_bf16_f32 v65, v70, v71
	v_ashrrev_i32_e32 v81, 31, v80
	v_cvt_pk_bf16_f32 v66, v66, v67
	v_cvt_pk_bf16_f32 v67, v72, v73
	ds_bpermute_b32 v212, v230, v64
	ds_bpermute_b32 v213, v230, v65
	ds_bpermute_b32 v214, v230, v66
	ds_bpermute_b32 v215, v230, v67
	s_waitcnt lgkmcnt(4)
; __device__ __forceinline__ unsigned cvt_pk_bf16(float lo, float hi) { unsigned r; asm volatile("v_cvt_pk_bf16_f32 %0, %1, %2" : "=v"(r) : "v"(lo), "v"(hi)); return r; }
;     __device__ __forceinline__ void operator()(const f32x4 (&acc)[2][2][4][2], const Unit& u, int wr, int wc, int fr, int fq) const {
;     ...
;                 const int row = row0 + ai * HALF + m * 16;
;                 const f32x4* sp = (const f32x4*)(ss + (size_t)row * 16);
;                 const f32x4 a0 = sp[0], a1 = sp[1], a2 = sp[2], a3 = sp[3];
;                 const float tot = ((a0.x + a0.y) + (a0.z + a0.w)) + ((a1.x + a1.y) + (a1.z + a1.w)) + ((a2.x + a2.y) + (a2.z + a2.w)) + ((a3.x + a3.y) + (a3.z + a3.w));
;                 const float rs = rsqrtf(tot * (1.0f / 1024.0f) + 1e-6f);
;                 bf16_t* rowp = O + (size_t)row * ldc + col0;
; #pragma unroll
;                 for (int bj = 0; bj < 2; ++bj) {
;                     f32x4 v0 = acc[ai][bj][m][0] * rs, v1 = acc[ai][bj][m][1] * rs;
;                     if (ACT == 1) {
; #pragma unroll
;                         for (int e = 0; e < 4; ++e) { float a = fmaxf(v0[e], 0.f); v0[e] = a * a; float b = fmaxf(v1[e], 0.f); v1[e] = b * b; }
;                     }
;                     u32x4 w; w.x = cvt_pk_bf16(v0[0], v0[1]); w.y = cvt_pk_bf16(v0[2], v0[3]); w.z = cvt_pk_bf16(v1[0], v1[1]); w.w = cvt_pk_bf16(v1[2], v1[3]);
;                     *(u32x4*)(rowp + bj * HALF) = w;
	global_store_dwordx4 v[82:83], v[208:211], off
	s_waitcnt lgkmcnt(0)
	global_store_dwordx4 v[82:83], v[212:215], off offset:256
	s_nop 1
	v_mad_i64_i32 v[66:67], s[24:25], v80, s49, 0
	v_lshl_add_u64 v[66:67], v[66:67], 1, s[78:79]
	v_lshl_add_u64 v[66:67], v[66:67], 0, v[152:153]
	v_mov_b32_e32 v64, v196
	v_pk_mul_f32 v[62:63], v[62:63], v[64:65] op_sel_hi:[1,0]
	v_pk_mul_f32 v[60:61], v[60:61], v[64:65] op_sel_hi:[1,0]
	v_pk_mul_f32 v[68:69], v[58:59], v[64:65] op_sel_hi:[1,0]
	v_pk_mul_f32 v[58:59], v[56:57], v[64:65] op_sel_hi:[1,0]
	v_cvt_pk_bf16_f32 v56, v60, v61
	v_cvt_pk_bf16_f32 v57, v62, v63
	v_pk_mul_f32 v[54:55], v[54:55], v[64:65] op_sel_hi:[1,0]
	v_cvt_pk_bf16_f32 v58, v58, v59
	v_cvt_pk_bf16_f32 v59, v68, v69
	ds_bpermute_b32 v208, v230, v56
	ds_bpermute_b32 v209, v230, v57
	ds_bpermute_b32 v210, v230, v58
	ds_bpermute_b32 v211, v230, v59
	v_pk_mul_f32 v[52:53], v[52:53], v[64:65] op_sel_hi:[1,0]
	s_nop 0
	v_pk_mul_f32 v[56:57], v[50:51], v[64:65] op_sel_hi:[1,0]
	v_pk_mul_f32 v[50:51], v[48:49], v[64:65] op_sel_hi:[1,0]
	v_add_u32_e32 v64, 0x90, v154
	v_cvt_pk_bf16_f32 v48, v52, v53
	v_cvt_pk_bf16_f32 v49, v54, v55
	v_ashrrev_i32_e32 v65, 31, v64
	v_cvt_pk_bf16_f32 v50, v50, v51
	v_cvt_pk_bf16_f32 v51, v56, v57
	ds_bpermute_b32 v212, v230, v48
	ds_bpermute_b32 v213, v230, v49
	ds_bpermute_b32 v214, v230, v50
	ds_bpermute_b32 v215, v230, v51
	s_waitcnt lgkmcnt(4)
	global_store_dwordx4 v[66:67], v[208:211], off
	s_waitcnt lgkmcnt(0)
	global_store_dwordx4 v[66:67], v[212:215], off offset:256
	s_nop 1
	v_mad_i64_i32 v[50:51], s[24:25], v64, s49, 0
	v_lshl_add_u64 v[50:51], v[50:51], 1, s[78:79]
	v_lshl_add_u64 v[50:51], v[50:51], 0, v[152:153]
	v_mov_b32_e32 v48, v200
	v_pk_mul_f32 v[46:47], v[46:47], v[48:49] op_sel_hi:[1,0]
	v_pk_mul_f32 v[44:45], v[44:45], v[48:49] op_sel_hi:[1,0]
	v_pk_mul_f32 v[52:53], v[42:43], v[48:49] op_sel_hi:[1,0]
	v_pk_mul_f32 v[42:43], v[40:41], v[48:49] op_sel_hi:[1,0]
	v_cvt_pk_bf16_f32 v40, v44, v45
	v_cvt_pk_bf16_f32 v41, v46, v47
	v_pk_mul_f32 v[38:39], v[38:39], v[48:49] op_sel_hi:[1,0]
	v_cvt_pk_bf16_f32 v42, v42, v43
	v_cvt_pk_bf16_f32 v43, v52, v53
	ds_bpermute_b32 v208, v230, v40
	ds_bpermute_b32 v209, v230, v41
	ds_bpermute_b32 v210, v230, v42
	ds_bpermute_b32 v211, v230, v43
	v_pk_mul_f32 v[36:37], v[36:37], v[48:49] op_sel_hi:[1,0]
	s_nop 0
	v_pk_mul_f32 v[40:41], v[34:35], v[48:49] op_sel_hi:[1,0]
	v_pk_mul_f32 v[34:35], v[32:33], v[48:49] op_sel_hi:[1,0]
	v_add_u32_e32 v48, 0xa0, v154
	v_cvt_pk_bf16_f32 v32, v36, v37
	v_cvt_pk_bf16_f32 v33, v38, v39
	v_ashrrev_i32_e32 v49, 31, v48
	v_cvt_pk_bf16_f32 v34, v34, v35
	v_cvt_pk_bf16_f32 v35, v40, v41
	ds_bpermute_b32 v212, v230, v32
	ds_bpermute_b32 v213, v230, v33
	ds_bpermute_b32 v214, v230, v34
	ds_bpermute_b32 v215, v230, v35
	s_waitcnt lgkmcnt(4)
	global_store_dwordx4 v[50:51], v[208:211], off
	s_waitcnt lgkmcnt(0)
	global_store_dwordx4 v[50:51], v[212:215], off offset:256
	s_nop 1
	v_mad_i64_i32 v[34:35], s[24:25], v48, s49, 0
	v_lshl_add_u64 v[34:35], v[34:35], 1, s[78:79]
	v_lshl_add_u64 v[34:35], v[34:35], 0, v[152:153]
	v_mov_b32_e32 v32, v216
	v_pk_mul_f32 v[30:31], v[30:31], v[32:33] op_sel_hi:[1,0]
	v_pk_mul_f32 v[28:29], v[28:29], v[32:33] op_sel_hi:[1,0]
	v_pk_mul_f32 v[36:37], v[26:27], v[32:33] op_sel_hi:[1,0]
	v_pk_mul_f32 v[26:27], v[24:25], v[32:33] op_sel_hi:[1,0]
	v_cvt_pk_bf16_f32 v24, v28, v29
	v_cvt_pk_bf16_f32 v25, v30, v31
	v_pk_mul_f32 v[22:23], v[22:23], v[32:33] op_sel_hi:[1,0]
	v_cvt_pk_bf16_f32 v26, v26, v27
	v_cvt_pk_bf16_f32 v27, v36, v37
	ds_bpermute_b32 v208, v230, v24
	ds_bpermute_b32 v209, v230, v25
	ds_bpermute_b32 v210, v230, v26
	ds_bpermute_b32 v211, v230, v27
	v_pk_mul_f32 v[20:21], v[20:21], v[32:33] op_sel_hi:[1,0]
	s_nop 0
	v_pk_mul_f32 v[24:25], v[18:19], v[32:33] op_sel_hi:[1,0]
	v_pk_mul_f32 v[18:19], v[16:17], v[32:33] op_sel_hi:[1,0]
	v_add_u32_e32 v32, 0xb0, v154
	v_cvt_pk_bf16_f32 v16, v20, v21
	v_cvt_pk_bf16_f32 v17, v22, v23
	v_ashrrev_i32_e32 v33, 31, v32
	v_cvt_pk_bf16_f32 v18, v18, v19
	v_cvt_pk_bf16_f32 v19, v24, v25
	ds_bpermute_b32 v212, v230, v16
	ds_bpermute_b32 v213, v230, v17
	ds_bpermute_b32 v214, v230, v18
	ds_bpermute_b32 v215, v230, v19
	s_waitcnt lgkmcnt(4)
	global_store_dwordx4 v[34:35], v[208:211], off
	s_waitcnt lgkmcnt(0)
	global_store_dwordx4 v[34:35], v[212:215], off offset:256
	s_nop 1
	v_mad_i64_i32 v[18:19], s[24:25], v32, s49, 0
	v_lshl_add_u64 v[18:19], v[18:19], 1, s[78:79]
	v_lshl_add_u64 v[18:19], v[18:19], 0, v[152:153]
	s_mov_b64 s[24:25], -1
	v_mov_b32_e32 v16, v220
	v_pk_mul_f32 v[14:15], v[14:15], v[16:17] op_sel_hi:[1,0]
	v_pk_mul_f32 v[12:13], v[12:13], v[16:17] op_sel_hi:[1,0]
	v_pk_mul_f32 v[20:21], v[10:11], v[16:17] op_sel_hi:[1,0]
	v_pk_mul_f32 v[10:11], v[8:9], v[16:17] op_sel_hi:[1,0]
	v_cvt_pk_bf16_f32 v8, v12, v13
	v_cvt_pk_bf16_f32 v9, v14, v15
	s_andn2_b64 vcc, exec, s[36:37]
	v_cvt_pk_bf16_f32 v10, v10, v11
	v_cvt_pk_bf16_f32 v11, v20, v21
	ds_bpermute_b32 v208, v230, v8
	ds_bpermute_b32 v209, v230, v9
	ds_bpermute_b32 v210, v230, v10
	ds_bpermute_b32 v211, v230, v11
	v_pk_mul_f32 v[6:7], v[6:7], v[16:17] op_sel_hi:[1,0]
	v_pk_mul_f32 v[4:5], v[4:5], v[16:17] op_sel_hi:[1,0]
	v_pk_mul_f32 v[8:9], v[2:3], v[16:17] op_sel_hi:[1,0]
	v_pk_mul_f32 v[2:3], v[0:1], v[16:17] op_sel_hi:[1,0]
	v_cvt_pk_bf16_f32 v0, v4, v5
	v_cvt_pk_bf16_f32 v1, v6, v7
	s_nop 0
	v_cvt_pk_bf16_f32 v2, v2, v3
	v_cvt_pk_bf16_f32 v3, v8, v9
	ds_bpermute_b32 v212, v230, v0
	ds_bpermute_b32 v213, v230, v1
	ds_bpermute_b32 v214, v230, v2
	ds_bpermute_b32 v215, v230, v3
	s_waitcnt lgkmcnt(4)
	global_store_dwordx4 v[18:19], v[208:211], off
	s_waitcnt lgkmcnt(0)
	global_store_dwordx4 v[18:19], v[212:215], off offset:256
	s_cbranch_vccnz .LBB0_422
	v_readlane_b32 s24, v250, 34
	v_readlane_b32 s25, v250, 35
	s_andn2_b64 vcc, exec, s[24:25]
	s_cbranch_vccnz .LBB0_421
	s_barrier
	s_branch .LBB0_421
